# stack6 + layer-0 in-proj epilogue no longer drains the next-unit prefetch before its stores (no operand loads on that path)
# speedup vs baseline: 1.0064x; 1.0001x over previous
; __device__ __forceinline__ u32x4 pack8(const f32x4 a, const f32x4 b) { u32x4 w; w.x = cvt_pk_bf16(a[0], a[1]); w.y = cvt_pk_bf16(a[2], a[3]); w.z = cvt_pk_bf16(b[0], b[1]); w.w = cvt_pk_bf16(b[2], b[3]); return w; }
;     __device__ __forceinline__ void operator()(const f32x4 (&acc)[2][2][4][2], const Unit& u, int wr, int wc, int fr_, int fq_) const {
;     ...
;         const bool isT = (pn == 1) || (pn == 2) || (pn == 3) || (pn == 10) || (pn == 11);
;         const bool isP = !(pn == 2 || pn == 3 || pn >= 10);
;         const int pcol0 = (pn < 2 ? pn : pn - 2) * 256;
;         bf16_t* tb[2];
; #pragma unroll
;         for (int bj = 0; bj < 2; ++bj) { const int col = bj * 128 + lc;
;             if (pn == 1) tb[bj] = KAT + ((size_t)(bl * 4 + (col >> 6)) * 64 + (col & 63)) * SEQ;
;             else if (pn < 4) { const int cv = (pn - 2) * 256 + col; tb[bj] = VAT + ((size_t)(bl * 4 + (cv >> 7)) * 128 + (cv & 127)) * SEQ; }
;             else { const int cv = (pn - 10) * 256 + col; tb[bj] = VBT + ((size_t)(bl * 8 + (cv >> 6)) * 64 + (cv & 63)) * SEQ; } }
; #pragma unroll
;         for (int ai = 0; ai < 2; ++ai) {
;             float mus[4], rss[4];
; #pragma unroll
;             for (int q = 0; q < 4; ++q) { mus[q] = 0.f; rss[q] = 1.f; if (st) row_stats(st, u.pm * 256 + ai * 128 + q * 16 + wr * 64 + fr, fq, mus[q], rss[q]); }
;             asm volatile("" ::: "memory");
; #pragma unroll
;             for (int m = 0; m < 4; ++m) {
;                 const int rt = ai * 128 + m * 16 + wr * 64 + fr, grow = u.pm * 256 + rt, tok = tok0 + rt;
;                 const float mu = mus[m], rs = rss[m];
; #pragma unroll
;                 for (int bj = 0; bj < 2; ++bj) {
;                     const f32x4 v0 = (acc[ai][bj][m][0] - mu * c1v[bj][0]) * rs + c2v[bj][0];
;                     const f32x4 v1 = (acc[ai][bj][m][1] - mu * c1v[bj][1]) * rs + c2v[bj][1];
;                     const int col = bj * 128 + lc;
;                     if (pn == 12) { if (col < 32) { *(f32x4*)(LR + (size_t)grow * 32 + col) = v0; *(f32x4*)(LR + (size_t)grow * 32 + col + 4) = v1; } }
;                     else {
;                         if (isP) *(u32x4*)(P + (size_t)grow * 2048 + pcol0 + col) = pack8(v0, v1);
.LBB0_235:
	s_and_b32 s1, s5, -2
	s_cmp_lt_i32 s5, 10
	s_cselect_b64 s[14:15], -1, 0
	s_cmp_lt_i32 s5, 2
	s_cselect_b32 s11, s5, s43
	s_cmp_lg_u32 s1, 2
	s_cselect_b64 s[16:17], -1, 0
	s_and_b64 s[16:17], s[14:15], s[16:17]
	s_lshl_b32 s58, s11, 8
	s_cmp_lg_u32 s5, 12
	s_cselect_b64 s[14:15], -1, 0
	s_ashr_i32 s59, s58, 31
	s_and_b32 s53, s51, 0x700
	s_cmp_lg_u64 s[48:49], 0
	s_cbranch_scc1 .Lskip_wait_inproj
	s_waitcnt vmcnt(0)
.Lskip_wait_inproj:
	v_xor_b32_e32 v167, 0x80000000, v61
	v_xor_b32_e32 v166, 0x80000000, v60
	v_and_b32_e32 v164, 1, v187
	v_bfe_i32 v165, v187, 0, 1
	v_ashrrev_i32_e32 v209, 31, v208
	s_cmp_lt_u32 s5, 12
	v_pk_fma_f32 v[160:161], v[166:167], v[144:145], v[160:161] op_sel_hi:[1,0,1]
	v_xor_b32_e32 v167, 0x80000000, v57
	v_xor_b32_e32 v166, 0x80000000, v56
	v_add_u32_e32 v183, s63, v187
	v_cmp_eq_u32_e64 s[42:43], 0, v164
	v_and_b32_e32 v190, 0x3ffe, v165
	v_lshlrev_b64 v[164:165], s0, v[208:209]
	s_cselect_b64 s[0:1], -1, 0
	s_lshr_b32 s5, 0xc0e, s5
	v_pk_fma_f32 v[156:157], v[166:167], v[144:145], v[156:157] op_sel_hi:[1,0,1]
	v_xor_b32_e32 v167, 0x80000000, v59
	v_xor_b32_e32 v166, 0x80000000, v58
	v_mov_b32_e32 v201, v202
	s_bitcmp1_b32 s5, 0
	v_add_u32_e32 v212, s51, v183
	v_xor_b32_e32 v63, 0x80000000, v63
	v_xor_b32_e32 v62, 0x80000000, v62
	v_pk_fma_f32 v[58:59], v[166:167], v[144:145], v[158:159] op_sel_hi:[1,0,1]
	s_cselect_b64 s[44:45], -1, 0
	v_add_u32_e32 v208, s53, v183
	v_ashrrev_i32_e32 v213, 31, v212
	v_pk_fma_f32 v[162:163], v[62:63], v[144:145], v[162:163] op_sel_hi:[1,0,1]
	v_pk_fma_f32 v[158:159], v[200:201], v[58:59], v[70:71] op_sel_hi:[0,1,1]
	v_cndmask_b32_e64 v58, 0, 1, s[16:17]
	v_readlane_b32 s4, v252, 43
	v_mov_b32_e32 v198, v189
	v_lshl_add_u64 v[164:165], v[210:211], 0, v[164:165]
	s_and_b64 s[60:61], s[0:1], s[44:45]
	v_lshlrev_b64 v[210:211], 12, v[212:213]
	v_ashrrev_i32_e32 v209, 31, v208
	v_pk_fma_f32 v[162:163], v[200:201], v[162:163], v[66:67] op_sel_hi:[0,1,1]
	v_pk_fma_f32 v[160:161], v[200:201], v[160:161], v[64:65] op_sel_hi:[0,1,1]
	v_pk_fma_f32 v[156:157], v[200:201], v[156:157], v[68:69] op_sel_hi:[0,1,1]
	s_mov_b64 s[0:1], -1
	s_and_b64 vcc, exec, s[14:15]
	v_cmp_ne_u32_e64 s[44:45], 1, v58
	v_readlane_b32 s5, v252, 44
	s_cbranch_vccz .LBB0_241
	s_and_b64 vcc, exec, s[44:45]
	s_cbranch_vccnz .LBB0_238
	v_lshl_add_u64 v[58:59], s[24:25], 0, v[210:211]
	v_lshl_add_u64 v[58:59], s[58:59], 1, v[58:59]
	v_cvt_pk_bf16_f32 v218, v160, v161
	v_cvt_pk_bf16_f32 v219, v162, v163
	v_cvt_pk_bf16_f32 v220, v156, v157
	v_cvt_pk_bf16_f32 v221, v158, v159
	v_lshl_add_u64 v[58:59], v[180:181], 1, v[58:59]
	global_store_dwordx4 v[58:59], v[218:221], off
